# last-shift-state copy loops (chunkB h==0, sample-scan h==0): all loads issued first, one wait, then the stores (was 4 / 13 serial round trips)
# baseline (speedup 1.0000x reference)
; __device__ __forceinline__ void chunkB_item(const Args& A, LAS unsigned char* lds, int tid, int lane, int wave, int bh) {
;     ...
;     if ((bh & 7) == 0) { const size_t row = (size_t)b * SEQ + SEQ - 1; float* so = A.out + OUT_SHP + (size_t)b * SHIFT;
;         for (int cix = tid; cix < SHIFT; cix += 512) so[cix] = bf2f(Z[row * NZ + cix]); }
.LBB0_284:
	v_mad_i64_i32 v[0:1], s[12:13], s14, v163, v[120:121]
	v_mad_i64_i32 v[2:3], s[12:13], s14, v173, v[122:123]
	global_load_ushort v4, v[0:1], off
	global_load_ushort v5, v[0:1], off offset:1024
	global_load_ushort v6, v[0:1], off offset:2048
	v_cmp_gt_u32_e32 vcc, 0x80, v144
	s_and_saveexec_b64 s[12:13], vcc
	global_load_ushort v7, v[0:1], off offset:3072
	s_or_b64 exec, exec, s[12:13]
	v_add_co_u32_e32 v8, vcc, 0x1000, v2
	s_nop 1
	v_addc_co_u32_e32 v9, vcc, 0, v3, vcc
	s_waitcnt vmcnt(0)
	v_lshlrev_b32_e32 v4, 16, v4
	v_lshlrev_b32_e32 v5, 16, v5
	v_lshlrev_b32_e32 v6, 16, v6
	v_lshlrev_b32_e32 v7, 16, v7
	global_store_dword v[2:3], v4, off
	global_store_dword v[2:3], v5, off offset:2048
	global_store_dword v[8:9], v6, off
	v_cmp_gt_u32_e32 vcc, 0x80, v144
	s_and_saveexec_b64 s[12:13], vcc
	global_store_dword v[8:9], v7, off offset:2048
	s_or_b64 exec, exec, s[12:13]
	s_branch .LBB0_269

; __device__ __forceinline__ void sscan_item(const Args& A, LAS unsigned char* lds, int tid, int lane, int wave, int bg, int h) {
;     ...
;     if (h == 0) { for (int c = tid; c < 4 * SHIFT; c += 512) { const int bi = c / SHIFT, cc = c % SHIFT, b = bg * 4 + bi; const size_t row = (size_t)MP + (size_t)b * 8 + 7;
;         A.out[OUT_SHS + (size_t)b * SHIFT + cc] = bf2f(Z[row * NZ + cc]); } }
.LBB0_429:
	v_add_u32_e32 v0, 0x0, v144
	v_mul_u32_u24_e32 v1, 0x4ec5, v0
	v_lshrrev_b32_e32 v1, 25, v1
	v_mul_u32_u24_e32 v4, 0x680, v1
	v_sub_u32_e32 v4, v0, v4
	v_add_u32_e32 v1, s64, v1
	v_mul_u32_u24_e32 v2, 0xe000, v1
	v_lshl_add_u32 v2, v4, 1, v2
	v_add_u32_e32 v2, 0xe00c400, v2
	global_load_ushort v236, v2, s[94:95]
	v_add_u32_e32 v0, 0x200, v144
	v_mul_u32_u24_e32 v1, 0x4ec5, v0
	v_lshrrev_b32_e32 v1, 25, v1
	v_mul_u32_u24_e32 v4, 0x680, v1
	v_sub_u32_e32 v4, v0, v4
	v_add_u32_e32 v1, s64, v1
	v_mul_u32_u24_e32 v2, 0xe000, v1
	v_lshl_add_u32 v2, v4, 1, v2
	v_add_u32_e32 v2, 0xe00c400, v2
	global_load_ushort v237, v2, s[94:95]
	v_add_u32_e32 v0, 0x400, v144
	v_mul_u32_u24_e32 v1, 0x4ec5, v0
	v_lshrrev_b32_e32 v1, 25, v1
	v_mul_u32_u24_e32 v4, 0x680, v1
	v_sub_u32_e32 v4, v0, v4
	v_add_u32_e32 v1, s64, v1
	v_mul_u32_u24_e32 v2, 0xe000, v1
	v_lshl_add_u32 v2, v4, 1, v2
	v_add_u32_e32 v2, 0xe00c400, v2
	global_load_ushort v238, v2, s[94:95]
	v_add_u32_e32 v0, 0x600, v144
	v_mul_u32_u24_e32 v1, 0x4ec5, v0
	v_lshrrev_b32_e32 v1, 25, v1
	v_mul_u32_u24_e32 v4, 0x680, v1
	v_sub_u32_e32 v4, v0, v4
	v_add_u32_e32 v1, s64, v1
	v_mul_u32_u24_e32 v2, 0xe000, v1
	v_lshl_add_u32 v2, v4, 1, v2
	v_add_u32_e32 v2, 0xe00c400, v2
	global_load_ushort v239, v2, s[94:95]
	v_add_u32_e32 v0, 0x800, v144
	v_mul_u32_u24_e32 v1, 0x4ec5, v0
	v_lshrrev_b32_e32 v1, 25, v1
	v_mul_u32_u24_e32 v4, 0x680, v1
	v_sub_u32_e32 v4, v0, v4
	v_add_u32_e32 v1, s64, v1
	v_mul_u32_u24_e32 v2, 0xe000, v1
	v_lshl_add_u32 v2, v4, 1, v2
	v_add_u32_e32 v2, 0xe00c400, v2
	global_load_ushort v240, v2, s[94:95]
	v_add_u32_e32 v0, 0xa00, v144
	v_mul_u32_u24_e32 v1, 0x4ec5, v0
	v_lshrrev_b32_e32 v1, 25, v1
	v_mul_u32_u24_e32 v4, 0x680, v1
	v_sub_u32_e32 v4, v0, v4
	v_add_u32_e32 v1, s64, v1
	v_mul_u32_u24_e32 v2, 0xe000, v1
	v_lshl_add_u32 v2, v4, 1, v2
	v_add_u32_e32 v2, 0xe00c400, v2
	global_load_ushort v241, v2, s[94:95]
	v_add_u32_e32 v0, 0xc00, v144
	v_mul_u32_u24_e32 v1, 0x4ec5, v0
	v_lshrrev_b32_e32 v1, 25, v1
	v_mul_u32_u24_e32 v4, 0x680, v1
	v_sub_u32_e32 v4, v0, v4
	v_add_u32_e32 v1, s64, v1
	v_mul_u32_u24_e32 v2, 0xe000, v1
	v_lshl_add_u32 v2, v4, 1, v2
	v_add_u32_e32 v2, 0xe00c400, v2
	global_load_ushort v242, v2, s[94:95]
	v_add_u32_e32 v0, 0xe00, v144
	v_mul_u32_u24_e32 v1, 0x4ec5, v0
	v_lshrrev_b32_e32 v1, 25, v1
	v_mul_u32_u24_e32 v4, 0x680, v1
	v_sub_u32_e32 v4, v0, v4
	v_add_u32_e32 v1, s64, v1
	v_mul_u32_u24_e32 v2, 0xe000, v1
	v_lshl_add_u32 v2, v4, 1, v2
	v_add_u32_e32 v2, 0xe00c400, v2
	global_load_ushort v243, v2, s[94:95]
	v_add_u32_e32 v0, 0x1000, v144
	v_mul_u32_u24_e32 v1, 0x4ec5, v0
	v_lshrrev_b32_e32 v1, 25, v1
	v_mul_u32_u24_e32 v4, 0x680, v1
	v_sub_u32_e32 v4, v0, v4
	v_add_u32_e32 v1, s64, v1
	v_mul_u32_u24_e32 v2, 0xe000, v1
	v_lshl_add_u32 v2, v4, 1, v2
	v_add_u32_e32 v2, 0xe00c400, v2
	global_load_ushort v244, v2, s[94:95]
	v_add_u32_e32 v0, 0x1200, v144
	v_mul_u32_u24_e32 v1, 0x4ec5, v0
	v_lshrrev_b32_e32 v1, 25, v1
	v_mul_u32_u24_e32 v4, 0x680, v1
	v_sub_u32_e32 v4, v0, v4
	v_add_u32_e32 v1, s64, v1
	v_mul_u32_u24_e32 v2, 0xe000, v1
	v_lshl_add_u32 v2, v4, 1, v2
	v_add_u32_e32 v2, 0xe00c400, v2
	global_load_ushort v245, v2, s[94:95]
	v_add_u32_e32 v0, 0x1400, v144
	v_mul_u32_u24_e32 v1, 0x4ec5, v0
	v_lshrrev_b32_e32 v1, 25, v1
	v_mul_u32_u24_e32 v4, 0x680, v1
	v_sub_u32_e32 v4, v0, v4
	v_add_u32_e32 v1, s64, v1
	v_mul_u32_u24_e32 v2, 0xe000, v1
	v_lshl_add_u32 v2, v4, 1, v2
	v_add_u32_e32 v2, 0xe00c400, v2
	global_load_ushort v246, v2, s[94:95]
	v_add_u32_e32 v0, 0x1600, v144
	v_mul_u32_u24_e32 v1, 0x4ec5, v0
	v_lshrrev_b32_e32 v1, 25, v1
	v_mul_u32_u24_e32 v4, 0x680, v1
	v_sub_u32_e32 v4, v0, v4
	v_add_u32_e32 v1, s64, v1
	v_mul_u32_u24_e32 v2, 0xe000, v1
	v_lshl_add_u32 v2, v4, 1, v2
	v_add_u32_e32 v2, 0xe00c400, v2
	global_load_ushort v247, v2, s[94:95]
	v_add_u32_e32 v0, 0x1800, v144
	v_mul_u32_u24_e32 v1, 0x4ec5, v0
	v_lshrrev_b32_e32 v1, 25, v1
	v_mul_u32_u24_e32 v4, 0x680, v1
	v_sub_u32_e32 v4, v0, v4
	v_add_u32_e32 v1, s64, v1
	v_mul_u32_u24_e32 v2, 0xe000, v1
	v_lshl_add_u32 v2, v4, 1, v2
	v_add_u32_e32 v2, 0xe00c400, v2
	global_load_ushort v250, v2, s[94:95]
	s_waitcnt vmcnt(0)
; __device__ __forceinline__ void sscan_item(const Args& A, LAS unsigned char* lds, int tid, int lane, int wave, int bg, int h) {
;     ...
;     if (h == 0) { for (int c = tid; c < 4 * SHIFT; c += 512) { const int bi = c / SHIFT, cc = c % SHIFT, b = bg * 4 + bi; const size_t row = (size_t)MP + (size_t)b * 8 + 7;
;         A.out[OUT_SHS + (size_t)b * SHIFT + cc] = bf2f(Z[row * NZ + cc]); } }
	v_add_u32_e32 v0, 0x0, v144
	v_mul_u32_u24_e32 v1, 0x4ec5, v0
	v_lshrrev_b32_e32 v1, 25, v1
	v_mul_u32_u24_e32 v4, 0x680, v1
	v_sub_u32_e32 v4, v0, v4
	v_add_u32_e32 v1, s64, v1
	v_mul_u32_u24_e32 v2, 0x1a00, v1
	v_lshl_add_u32 v2, v4, 2, v2
	v_add_u32_e32 v2, 0x981a000, v2
	v_lshlrev_b32_e32 v3, 16, v236
	global_store_dword v2, v3, s[86:87]
	v_add_u32_e32 v0, 0x200, v144
	v_mul_u32_u24_e32 v1, 0x4ec5, v0
	v_lshrrev_b32_e32 v1, 25, v1
	v_mul_u32_u24_e32 v4, 0x680, v1
	v_sub_u32_e32 v4, v0, v4
	v_add_u32_e32 v1, s64, v1
	v_mul_u32_u24_e32 v2, 0x1a00, v1
	v_lshl_add_u32 v2, v4, 2, v2
	v_add_u32_e32 v2, 0x981a000, v2
	v_lshlrev_b32_e32 v3, 16, v237
	global_store_dword v2, v3, s[86:87]
	v_add_u32_e32 v0, 0x400, v144
	v_mul_u32_u24_e32 v1, 0x4ec5, v0
	v_lshrrev_b32_e32 v1, 25, v1
	v_mul_u32_u24_e32 v4, 0x680, v1
	v_sub_u32_e32 v4, v0, v4
	v_add_u32_e32 v1, s64, v1
	v_mul_u32_u24_e32 v2, 0x1a00, v1
	v_lshl_add_u32 v2, v4, 2, v2
	v_add_u32_e32 v2, 0x981a000, v2
	v_lshlrev_b32_e32 v3, 16, v238
	global_store_dword v2, v3, s[86:87]
	v_add_u32_e32 v0, 0x600, v144
	v_mul_u32_u24_e32 v1, 0x4ec5, v0
	v_lshrrev_b32_e32 v1, 25, v1
	v_mul_u32_u24_e32 v4, 0x680, v1
	v_sub_u32_e32 v4, v0, v4
	v_add_u32_e32 v1, s64, v1
	v_mul_u32_u24_e32 v2, 0x1a00, v1
	v_lshl_add_u32 v2, v4, 2, v2
	v_add_u32_e32 v2, 0x981a000, v2
	v_lshlrev_b32_e32 v3, 16, v239
	global_store_dword v2, v3, s[86:87]
	v_add_u32_e32 v0, 0x800, v144
	v_mul_u32_u24_e32 v1, 0x4ec5, v0
	v_lshrrev_b32_e32 v1, 25, v1
	v_mul_u32_u24_e32 v4, 0x680, v1
	v_sub_u32_e32 v4, v0, v4
	v_add_u32_e32 v1, s64, v1
	v_mul_u32_u24_e32 v2, 0x1a00, v1
	v_lshl_add_u32 v2, v4, 2, v2
	v_add_u32_e32 v2, 0x981a000, v2
	v_lshlrev_b32_e32 v3, 16, v240
	global_store_dword v2, v3, s[86:87]
	v_add_u32_e32 v0, 0xa00, v144
	v_mul_u32_u24_e32 v1, 0x4ec5, v0
	v_lshrrev_b32_e32 v1, 25, v1
	v_mul_u32_u24_e32 v4, 0x680, v1
	v_sub_u32_e32 v4, v0, v4
	v_add_u32_e32 v1, s64, v1
	v_mul_u32_u24_e32 v2, 0x1a00, v1
	v_lshl_add_u32 v2, v4, 2, v2
	v_add_u32_e32 v2, 0x981a000, v2
	v_lshlrev_b32_e32 v3, 16, v241
	global_store_dword v2, v3, s[86:87]
	v_add_u32_e32 v0, 0xc00, v144
	v_mul_u32_u24_e32 v1, 0x4ec5, v0
	v_lshrrev_b32_e32 v1, 25, v1
	v_mul_u32_u24_e32 v4, 0x680, v1
	v_sub_u32_e32 v4, v0, v4
	v_add_u32_e32 v1, s64, v1
	v_mul_u32_u24_e32 v2, 0x1a00, v1
	v_lshl_add_u32 v2, v4, 2, v2
	v_add_u32_e32 v2, 0x981a000, v2
	v_lshlrev_b32_e32 v3, 16, v242
	global_store_dword v2, v3, s[86:87]
	v_add_u32_e32 v0, 0xe00, v144
	v_mul_u32_u24_e32 v1, 0x4ec5, v0
	v_lshrrev_b32_e32 v1, 25, v1
	v_mul_u32_u24_e32 v4, 0x680, v1
	v_sub_u32_e32 v4, v0, v4
	v_add_u32_e32 v1, s64, v1
	v_mul_u32_u24_e32 v2, 0x1a00, v1
	v_lshl_add_u32 v2, v4, 2, v2
	v_add_u32_e32 v2, 0x981a000, v2
	v_lshlrev_b32_e32 v3, 16, v243
	global_store_dword v2, v3, s[86:87]
	v_add_u32_e32 v0, 0x1000, v144
	v_mul_u32_u24_e32 v1, 0x4ec5, v0
	v_lshrrev_b32_e32 v1, 25, v1
	v_mul_u32_u24_e32 v4, 0x680, v1
	v_sub_u32_e32 v4, v0, v4
	v_add_u32_e32 v1, s64, v1
	v_mul_u32_u24_e32 v2, 0x1a00, v1
	v_lshl_add_u32 v2, v4, 2, v2
	v_add_u32_e32 v2, 0x981a000, v2
	v_lshlrev_b32_e32 v3, 16, v244
	global_store_dword v2, v3, s[86:87]
	v_add_u32_e32 v0, 0x1200, v144
	v_mul_u32_u24_e32 v1, 0x4ec5, v0
	v_lshrrev_b32_e32 v1, 25, v1
	v_mul_u32_u24_e32 v4, 0x680, v1
	v_sub_u32_e32 v4, v0, v4
	v_add_u32_e32 v1, s64, v1
	v_mul_u32_u24_e32 v2, 0x1a00, v1
	v_lshl_add_u32 v2, v4, 2, v2
	v_add_u32_e32 v2, 0x981a000, v2
	v_lshlrev_b32_e32 v3, 16, v245
	global_store_dword v2, v3, s[86:87]
	v_add_u32_e32 v0, 0x1400, v144
	v_mul_u32_u24_e32 v1, 0x4ec5, v0
	v_lshrrev_b32_e32 v1, 25, v1
	v_mul_u32_u24_e32 v4, 0x680, v1
	v_sub_u32_e32 v4, v0, v4
	v_add_u32_e32 v1, s64, v1
	v_mul_u32_u24_e32 v2, 0x1a00, v1
	v_lshl_add_u32 v2, v4, 2, v2
	v_add_u32_e32 v2, 0x981a000, v2
	v_lshlrev_b32_e32 v3, 16, v246
	global_store_dword v2, v3, s[86:87]
	v_add_u32_e32 v0, 0x1600, v144
	v_mul_u32_u24_e32 v1, 0x4ec5, v0
	v_lshrrev_b32_e32 v1, 25, v1
	v_mul_u32_u24_e32 v4, 0x680, v1
	v_sub_u32_e32 v4, v0, v4
	v_add_u32_e32 v1, s64, v1
	v_mul_u32_u24_e32 v2, 0x1a00, v1
	v_lshl_add_u32 v2, v4, 2, v2
	v_add_u32_e32 v2, 0x981a000, v2
	v_lshlrev_b32_e32 v3, 16, v247
	global_store_dword v2, v3, s[86:87]
	v_add_u32_e32 v0, 0x1800, v144
	v_mul_u32_u24_e32 v1, 0x4ec5, v0
	v_lshrrev_b32_e32 v1, 25, v1
	v_mul_u32_u24_e32 v4, 0x680, v1
	v_sub_u32_e32 v4, v0, v4
	v_add_u32_e32 v1, s64, v1
	v_mul_u32_u24_e32 v2, 0x1a00, v1
	v_lshl_add_u32 v2, v4, 2, v2
	v_add_u32_e32 v2, 0x981a000, v2
	v_lshlrev_b32_e32 v3, 16, v250
	global_store_dword v2, v3, s[86:87]
	s_branch .LBB0_318
